# band attention near tiles (chunk distance 0/1): bias gather issued as 16 ds_read2_b32 from one base register instead of 32 ds_read_b32
# speedup vs baseline: 1.0025x; 1.0025x over previous
.LBB0_454:
	s_cmp_le_i32 s23, s62
	s_cselect_b64 s[60:61], -1, 0
	s_cmp_ge_i32 s23, s63
	s_cselect_b64 s[66:67], -1, 0
	s_and_b64 s[60:61], s[60:61], s[66:67]
	s_andn2_b64 vcc, exec, s[60:61]
	s_cbranch_vccnz .LBB0_462
	ds_read_b32 v220, v3 offset:22528
	ds_read_b128 v[4:7], v165
	ds_read_b128 v[8:11], v165 offset:32
	ds_read_b128 v[12:15], v165 offset:4608
	ds_read_b128 v[130:133], v165 offset:64
	ds_read_b128 v[134:137], v165 offset:4640
	ds_read_b128 v[138:141], v165 offset:4672
	s_waitcnt lgkmcnt(5)
	v_mfma_f32_32x32x16_bf16 v[50:65], v[4:7], v[82:85], 0
	ds_read_b128 v[4:7], v165 offset:96
	ds_read_b128 v[142:145], v165 offset:4704
	s_waitcnt lgkmcnt(5)
	v_mfma_f32_32x32x16_bf16 v[66:81], v[12:15], v[82:85], 0
	v_mfma_f32_32x32x16_bf16 v[50:65], v[8:11], v[86:89], v[50:65]
	s_waitcnt lgkmcnt(3)
	v_mfma_f32_32x32x16_bf16 v[66:81], v[134:137], v[86:89], v[66:81]
	v_mfma_f32_32x32x16_bf16 v[50:65], v[130:133], v[90:93], v[50:65]
	s_waitcnt lgkmcnt(2)
	v_mfma_f32_32x32x16_bf16 v[66:81], v[138:141], v[90:93], v[66:81]
	s_waitcnt lgkmcnt(1)
	v_mfma_f32_32x32x16_bf16 v[50:65], v[4:7], v[94:97], v[50:65]
	s_waitcnt lgkmcnt(0)
	v_mfma_f32_32x32x16_bf16 v[66:81], v[142:145], v[94:97], v[66:81]
	s_cmp_lt_i32 s64, 3
	s_mov_b64 s[60:61], -1
	s_cbranch_scc0 .LBB0_457
	v_lshlrev_b32_e32 v186, 2, v119
	s_cmp_lt_i32 s64, 2
	s_cbranch_scc0 .Lbg_clamp
	v_add_u32_e32 v187, 0x5324, v186
	ds_read2_b32 v[4:5], v187 offset0:55 offset1:54
	ds_read2_b32 v[6:7], v187 offset0:53 offset1:52
	ds_read2_b32 v[8:9], v187 offset0:51 offset1:50
	ds_read2_b32 v[10:11], v187 offset0:49 offset1:48
	ds_read2_b32 v[12:13], v187 offset0:39 offset1:38
	ds_read2_b32 v[14:15], v187 offset0:37 offset1:36
	ds_read2_b32 v[130:131], v187 offset0:35 offset1:34
	ds_read2_b32 v[16:17], v187 offset0:33 offset1:32
	ds_read2_b32 v[136:137], v187 offset0:23 offset1:22
	ds_read2_b32 v[132:133], v187 offset0:21 offset1:20
	ds_read2_b32 v[174:175], v187 offset0:19 offset1:18
	ds_read2_b32 v[176:177], v187 offset0:17 offset1:16
	ds_read2_b32 v[178:179], v187 offset0:7 offset1:6
	ds_read2_b32 v[180:181], v187 offset0:5 offset1:4
	ds_read2_b32 v[182:183], v187 offset0:3 offset1:2
	ds_read2_b32 v[184:185], v187 offset0:1 offset1:0
	s_waitcnt lgkmcnt(8)
	s_branch .Lbg_tail
